# HGRN chunk-summary outer-product loop: LDS operand reads software-pipelined two steps ahead with three register sets, in-place packed FMA accumulators
# baseline (speedup 1.0000x reference)
; DI void hgrn_h1(const Params& p, int l, int item, char* lds) {
;     ...
;   const int dblk = tid >> 4, eblk = tid & 15;
;   float au[4][4];
; #pragma unroll
;   for (int i = 0; i < 4; ++i)
; #pragma unroll
;     for (int j = 0; j < 4; ++j) au[i][j] = 0.f;
;   for (int s = 0; s < 64; ++s) {
;     const f32x4 a4 = *(const f32x4*)(QS + s * HP + 4 * dblk), v4 = *(const f32x4*)(V + s * HP + 4 * eblk);
;     const float aa[4] = {a4.x, a4.y, a4.z, a4.w}, vv[4] = {v4.x, v4.y, v4.z, v4.w};
; #pragma unroll
;     for (int i = 0; i < 4; ++i)
; #pragma unroll
;       for (int j = 0; j < 4; ++j) au[i][j] += aa[i] * vv[j];
;   }
;   float* uo = p.U + (size_t)item * 4096;
; #pragma unroll
;   for (int i = 0; i < 4; ++i) *(f32x4*)(uo + (4 * dblk + i) * 64 + 4 * eblk) = (f32x4){au[i][0], au[i][1], au[i][2], au[i][3]};
.LBB0_828:
	v_add_u32_e32 v38, s2, v0
	v_add_u32_e32 v39, s2, v25
	ds_read_b128 v[40:43], v38
	ds_read_b128 v[44:47], v39
	ds_read_b128 v[48:51], v38 offset:272
	ds_read_b128 v[52:55], v39 offset:272
	s_addk_i32 s2, 0x880
	s_cmpk_lg_i32 s2, 0x4400
	s_waitcnt lgkmcnt(2)
	ds_read_b128 v[56:59], v38 offset:544
	ds_read_b128 v[60:63], v39 offset:544
	v_pk_fma_f32 v[6:7], v[40:41], v[44:45], v[6:7] op_sel_hi:[0,1,1]
	v_pk_fma_f32 v[8:9], v[40:41], v[46:47], v[8:9] op_sel_hi:[0,1,1]
	v_pk_fma_f32 v[14:15], v[40:41], v[44:45], v[14:15] op_sel:[1,0,0]
	v_pk_fma_f32 v[16:17], v[40:41], v[46:47], v[16:17] op_sel:[1,0,0]
	v_pk_fma_f32 v[10:11], v[42:43], v[44:45], v[10:11] op_sel_hi:[0,1,1]
	v_pk_fma_f32 v[12:13], v[42:43], v[46:47], v[12:13] op_sel_hi:[0,1,1]
	v_pk_fma_f32 v[2:3], v[42:43], v[44:45], v[2:3] op_sel:[1,0,0]
	v_pk_fma_f32 v[4:5], v[42:43], v[46:47], v[4:5] op_sel:[1,0,0]
	s_waitcnt lgkmcnt(2)
	ds_read_b128 v[40:43], v38 offset:816
	ds_read_b128 v[44:47], v39 offset:816
	v_pk_fma_f32 v[6:7], v[48:49], v[52:53], v[6:7] op_sel_hi:[0,1,1]
	v_pk_fma_f32 v[8:9], v[48:49], v[54:55], v[8:9] op_sel_hi:[0,1,1]
	v_pk_fma_f32 v[14:15], v[48:49], v[52:53], v[14:15] op_sel:[1,0,0]
	v_pk_fma_f32 v[16:17], v[48:49], v[54:55], v[16:17] op_sel:[1,0,0]
	v_pk_fma_f32 v[10:11], v[50:51], v[52:53], v[10:11] op_sel_hi:[0,1,1]
	v_pk_fma_f32 v[12:13], v[50:51], v[54:55], v[12:13] op_sel_hi:[0,1,1]
	v_pk_fma_f32 v[2:3], v[50:51], v[52:53], v[2:3] op_sel:[1,0,0]
	v_pk_fma_f32 v[4:5], v[50:51], v[54:55], v[4:5] op_sel:[1,0,0]
	s_waitcnt lgkmcnt(2)
	ds_read_b128 v[48:51], v38 offset:1088
	ds_read_b128 v[52:55], v39 offset:1088
	v_pk_fma_f32 v[6:7], v[56:57], v[60:61], v[6:7] op_sel_hi:[0,1,1]
	v_pk_fma_f32 v[8:9], v[56:57], v[62:63], v[8:9] op_sel_hi:[0,1,1]
	v_pk_fma_f32 v[14:15], v[56:57], v[60:61], v[14:15] op_sel:[1,0,0]
	v_pk_fma_f32 v[16:17], v[56:57], v[62:63], v[16:17] op_sel:[1,0,0]
	v_pk_fma_f32 v[10:11], v[58:59], v[60:61], v[10:11] op_sel_hi:[0,1,1]
	v_pk_fma_f32 v[12:13], v[58:59], v[62:63], v[12:13] op_sel_hi:[0,1,1]
	v_pk_fma_f32 v[2:3], v[58:59], v[60:61], v[2:3] op_sel:[1,0,0]
	v_pk_fma_f32 v[4:5], v[58:59], v[62:63], v[4:5] op_sel:[1,0,0]
	s_waitcnt lgkmcnt(2)
	ds_read_b128 v[56:59], v38 offset:1360
	ds_read_b128 v[60:63], v39 offset:1360
	v_pk_fma_f32 v[6:7], v[40:41], v[44:45], v[6:7] op_sel_hi:[0,1,1]
	v_pk_fma_f32 v[8:9], v[40:41], v[46:47], v[8:9] op_sel_hi:[0,1,1]
	v_pk_fma_f32 v[14:15], v[40:41], v[44:45], v[14:15] op_sel:[1,0,0]
	v_pk_fma_f32 v[16:17], v[40:41], v[46:47], v[16:17] op_sel:[1,0,0]
	v_pk_fma_f32 v[10:11], v[42:43], v[44:45], v[10:11] op_sel_hi:[0,1,1]
	v_pk_fma_f32 v[12:13], v[42:43], v[46:47], v[12:13] op_sel_hi:[0,1,1]
	v_pk_fma_f32 v[2:3], v[42:43], v[44:45], v[2:3] op_sel:[1,0,0]
	v_pk_fma_f32 v[4:5], v[42:43], v[46:47], v[4:5] op_sel:[1,0,0]
	s_waitcnt lgkmcnt(2)
	ds_read_b128 v[40:43], v38 offset:1632
	ds_read_b128 v[44:47], v39 offset:1632
	v_pk_fma_f32 v[6:7], v[48:49], v[52:53], v[6:7] op_sel_hi:[0,1,1]
	v_pk_fma_f32 v[8:9], v[48:49], v[54:55], v[8:9] op_sel_hi:[0,1,1]
	v_pk_fma_f32 v[14:15], v[48:49], v[52:53], v[14:15] op_sel:[1,0,0]
	v_pk_fma_f32 v[16:17], v[48:49], v[54:55], v[16:17] op_sel:[1,0,0]
	v_pk_fma_f32 v[10:11], v[50:51], v[52:53], v[10:11] op_sel_hi:[0,1,1]
	v_pk_fma_f32 v[12:13], v[50:51], v[54:55], v[12:13] op_sel_hi:[0,1,1]
	v_pk_fma_f32 v[2:3], v[50:51], v[52:53], v[2:3] op_sel:[1,0,0]
	v_pk_fma_f32 v[4:5], v[50:51], v[54:55], v[4:5] op_sel:[1,0,0]
	s_waitcnt lgkmcnt(2)
	ds_read_b128 v[48:51], v38 offset:1904
	ds_read_b128 v[52:55], v39 offset:1904
	v_pk_fma_f32 v[6:7], v[56:57], v[60:61], v[6:7] op_sel_hi:[0,1,1]
	v_pk_fma_f32 v[8:9], v[56:57], v[62:63], v[8:9] op_sel_hi:[0,1,1]
	v_pk_fma_f32 v[14:15], v[56:57], v[60:61], v[14:15] op_sel:[1,0,0]
	v_pk_fma_f32 v[16:17], v[56:57], v[62:63], v[16:17] op_sel:[1,0,0]
	v_pk_fma_f32 v[10:11], v[58:59], v[60:61], v[10:11] op_sel_hi:[0,1,1]
	v_pk_fma_f32 v[12:13], v[58:59], v[62:63], v[12:13] op_sel_hi:[0,1,1]
	v_pk_fma_f32 v[2:3], v[58:59], v[60:61], v[2:3] op_sel:[1,0,0]
	v_pk_fma_f32 v[4:5], v[58:59], v[62:63], v[4:5] op_sel:[1,0,0]
	s_waitcnt lgkmcnt(2)
	v_pk_fma_f32 v[6:7], v[40:41], v[44:45], v[6:7] op_sel_hi:[0,1,1]
	v_pk_fma_f32 v[8:9], v[40:41], v[46:47], v[8:9] op_sel_hi:[0,1,1]
	v_pk_fma_f32 v[14:15], v[40:41], v[44:45], v[14:15] op_sel:[1,0,0]
	v_pk_fma_f32 v[16:17], v[40:41], v[46:47], v[16:17] op_sel:[1,0,0]
	v_pk_fma_f32 v[10:11], v[42:43], v[44:45], v[10:11] op_sel_hi:[0,1,1]
	v_pk_fma_f32 v[12:13], v[42:43], v[46:47], v[12:13] op_sel_hi:[0,1,1]
	v_pk_fma_f32 v[2:3], v[42:43], v[44:45], v[2:3] op_sel:[1,0,0]
	v_pk_fma_f32 v[4:5], v[42:43], v[46:47], v[4:5] op_sel:[1,0,0]
	s_waitcnt lgkmcnt(0)
	v_pk_fma_f32 v[6:7], v[48:49], v[52:53], v[6:7] op_sel_hi:[0,1,1]
	v_pk_fma_f32 v[8:9], v[48:49], v[54:55], v[8:9] op_sel_hi:[0,1,1]
	v_pk_fma_f32 v[14:15], v[48:49], v[52:53], v[14:15] op_sel:[1,0,0]
	v_pk_fma_f32 v[16:17], v[48:49], v[54:55], v[16:17] op_sel:[1,0,0]
	v_pk_fma_f32 v[10:11], v[50:51], v[52:53], v[10:11] op_sel_hi:[0,1,1]
	v_pk_fma_f32 v[12:13], v[50:51], v[54:55], v[12:13] op_sel_hi:[0,1,1]
	v_pk_fma_f32 v[2:3], v[50:51], v[52:53], v[2:3] op_sel:[1,0,0]
	v_pk_fma_f32 v[4:5], v[50:51], v[54:55], v[4:5] op_sel:[1,0,0]
	s_cbranch_scc1 .LBB0_828
	v_readlane_b32 s40, v253, 0
	v_lshlrev_b64 v[18:19], 14, v[18:19]
	v_readlane_b32 s41, v253, 1
	v_and_b32_e32 v0, 0xf0, v24
	s_add_i32 s6, s6, s88
	v_lshl_add_u64 v[18:19], s[40:41], 0, v[18:19]
	v_lshl_add_u64 v[18:19], v[18:19], 0, v[0:1]
	v_lshlrev_b32_sdwa v0, v248, v23 dst_sel:DWORD dst_unused:UNUSED_PAD src0_sel:DWORD src1_sel:BYTE_0
	v_and_b32_e32 v0, 0x3c00, v0
	v_lshl_add_u64 v[18:19], v[18:19], 0, v[0:1]
	s_cmpk_gt_i32 s6, 0x7ff
	v_readlane_b32 s42, v253, 2
	v_readlane_b32 s43, v253, 3
	global_store_dwordx4 v[18:19], v[6:9], off
	global_store_dwordx4 v[18:19], v[14:17], off offset:256
	global_store_dwordx4 v[18:19], v[10:13], off offset:512
	global_store_dwordx4 v[18:19], v[2:5], off offset:768
	s_cbranch_scc0 .LBB0_755
